# v35 + gate_phase: w_f (128KB) staged once per workgroup into LDS by coalesced global_load_lds with a row/chunk swizzle, j-loop reads it with conflict-free ds_read_b128 instead of 16 uncoalesced global
# speedup vs baseline: 1.0062x; 1.0062x over previous
.LBB0_201:
	v_mov_b32_e32 v0, v210
	s_mov_b32 s2, s73
	v_readfirstlane_b32 s0, v0
	s_ashr_i32 s1, s0, 6
	s_mov_b32 s0, s80
	s_lshl_b32 s2, s2, 3
	s_add_i32 s1, s2, s1
	s_cmpk_gt_i32 s1, 0x100f
	s_load_dwordx2 s[44:45], s[74:75], 0x98
	s_waitcnt lgkmcnt(0)
	s_load_dwordx2 s[38:39], s[74:75], 48
	s_waitcnt lgkmcnt(0)
	s_load_dwordx2 s[46:47], s[74:75], 0x48
	s_waitcnt lgkmcnt(0)
	s_load_dwordx2 s[48:49], s[74:75], 0x50
	s_waitcnt lgkmcnt(0)
	s_cbranch_scc1 .LBB0_222
	v_readfirstlane_b32 vcc_lo, v210
	v_lshrrev_b32_e32 v216, 4, v214
	v_bfe_u32 v217, v214, 2, 2
	v_sub_u32_e32 v217, v217, v216
	v_and_b32_e32 v217, 3, v217
	v_lshlrev_b32_e32 v217, 6, v217
	v_lshl_add_u32 v217, v216, 8, v217
	v_and_b32_e32 v218, 3, v214
	v_add_u32_e32 v219, 0, v218
	v_and_b32_e32 v219, 3, v219
	v_lshl_add_u32 v192, v219, 4, v217
	v_add_u32_e32 v219, 3, v218
	v_and_b32_e32 v219, 3, v219
	v_lshl_add_u32 v193, v219, 4, v217
	v_add_u32_e32 v219, 2, v218
	v_and_b32_e32 v219, 3, v219
	v_lshl_add_u32 v194, v219, 4, v217
	v_add_u32_e32 v219, 1, v218
	v_and_b32_e32 v219, 3, v219
	v_lshl_add_u32 v195, v219, 4, v217
	s_lshr_b32 vcc_lo, vcc_lo, 6
	s_lshl_b32 s94, vcc_lo, 14
	s_add_u32 s98, s46, s94
	s_addc_u32 s99, s47, 0
	s_add_i32 m0, s94, 0x0
	s_nop 0
	global_load_lds_dwordx4 v192, s[98:99]
	global_load_lds_dwordx4 v193, s[98:99] offset:1024
	global_load_lds_dwordx4 v194, s[98:99] offset:2048
	global_load_lds_dwordx4 v195, s[98:99] offset:3072
	s_add_u32 s98, s98, 0x1000
	s_addc_u32 s99, s99, 0
	s_add_i32 m0, s94, 0x1000
	s_nop 0
	global_load_lds_dwordx4 v192, s[98:99]
	global_load_lds_dwordx4 v193, s[98:99] offset:1024
	global_load_lds_dwordx4 v194, s[98:99] offset:2048
	global_load_lds_dwordx4 v195, s[98:99] offset:3072
	s_add_u32 s98, s98, 0x1000
	s_addc_u32 s99, s99, 0
	s_add_i32 m0, s94, 0x2000
	s_nop 0
	global_load_lds_dwordx4 v192, s[98:99]
	global_load_lds_dwordx4 v193, s[98:99] offset:1024
	global_load_lds_dwordx4 v194, s[98:99] offset:2048
	global_load_lds_dwordx4 v195, s[98:99] offset:3072
	s_add_u32 s98, s98, 0x1000
	s_addc_u32 s99, s99, 0
	s_add_i32 m0, s94, 0x3000
	s_nop 0
	global_load_lds_dwordx4 v192, s[98:99]
	global_load_lds_dwordx4 v193, s[98:99] offset:1024
	global_load_lds_dwordx4 v194, s[98:99] offset:2048
	global_load_lds_dwordx4 v195, s[98:99] offset:3072
	v_lshlrev_b32_e32 v220, 8, v214
	v_add_u32_e32 v220, 0xffffc000, v220
	v_lshrrev_b32_e32 v221, 2, v214
	v_add_u32_e32 v219, 0, v214
	v_and_b32_e32 v219, 3, v219
	v_lshl_add_u32 v222, v219, 6, v220
	v_add_u32_e32 v219, 1, v214
	v_and_b32_e32 v219, 3, v219
	v_lshl_add_u32 v223, v219, 6, v220
	v_add_u32_e32 v219, 2, v214
	v_and_b32_e32 v219, 3, v219
	v_lshl_add_u32 v224, v219, 6, v220
	v_add_u32_e32 v219, 3, v214
	v_and_b32_e32 v219, 3, v219
	v_lshl_add_u32 v225, v219, 6, v220
	v_add_u32_e32 v219, 0, v221
	v_and_b32_e32 v219, 3, v219
	v_lshlrev_b32_e32 v226, 4, v219
	v_add_u32_e32 v219, 1, v221
	v_and_b32_e32 v219, 3, v219
	v_lshlrev_b32_e32 v227, 4, v219
	v_add_u32_e32 v219, 2, v221
	v_and_b32_e32 v219, 3, v219
	v_lshlrev_b32_e32 v228, 4, v219
	v_add_u32_e32 v219, 3, v221
	v_and_b32_e32 v219, 3, v219
	v_lshlrev_b32_e32 v229, 4, v219
	v_add_u32_e32 v196, v222, v226
	v_add_u32_e32 v197, v222, v227
	v_add_u32_e32 v198, v222, v228
	v_add_u32_e32 v199, v222, v229
	v_add_u32_e32 v200, v223, v226
	v_add_u32_e32 v201, v223, v227
	v_add_u32_e32 v202, v223, v228
	v_add_u32_e32 v203, v223, v229
	v_add_u32_e32 v204, v224, v226
	v_add_u32_e32 v205, v224, v227
	v_add_u32_e32 v206, v224, v228
	v_add_u32_e32 v207, v224, v229
	v_add_u32_e32 v208, v225, v226
	v_add_u32_e32 v209, v225, v227
	v_add_u32_e32 v232, v225, v228
	v_add_u32_e32 v233, v225, v229
	s_waitcnt vmcnt(0)
	s_barrier
	v_and_b32_e32 v10, 63, v0
	v_and_b32_e32 v0, 64, v214
	v_add_u32_e32 v0, 64, v0
	v_xor_b32_e32 v1, 1, v214
	v_cmp_lt_i32_e64 s[2:3], v1, v0
	v_lshlrev_b32_e32 v128, 2, v10
	s_lshl_b32 s40, s0, 5
	v_cndmask_b32_e64 v1, v214, v1, s[2:3]
	v_lshlrev_b32_e32 v88, 2, v1
	v_xor_b32_e32 v1, 2, v214
	v_cmp_lt_i32_e64 s[2:3], v1, v0
	s_lshl_b32 s42, s1, 2
	v_lshl_add_u64 v[2:3], s[44:45], 0, v[128:129]
	v_cndmask_b32_e64 v1, v214, v1, s[2:3]
	v_lshlrev_b32_e32 v89, 2, v1
	v_xor_b32_e32 v1, 4, v214
	v_cmp_lt_i32_e64 s[2:3], v1, v0
	s_mov_b64 s[0:1], 0x23b08000
	s_ashr_i32 s43, s42, 31
	v_cndmask_b32_e64 v1, v214, v1, s[2:3]
	v_lshlrev_b32_e32 v90, 2, v1
	v_xor_b32_e32 v1, 8, v214
	v_cmp_lt_i32_e64 s[2:3], v1, v0
	v_lshl_add_u64 v[4:5], s[48:49], 0, v[128:129]
	v_lshlrev_b32_e32 v128, 8, v10
	v_cndmask_b32_e64 v1, v214, v1, s[2:3]
	v_lshlrev_b32_e32 v91, 2, v1
	v_xor_b32_e32 v1, 16, v214
	v_cmp_lt_i32_e64 s[2:3], v1, v0
	v_lshl_add_u64 v[6:7], s[46:47], 0, v[128:129]
	v_lshlrev_b32_e32 v128, 3, v10
	v_cndmask_b32_e64 v1, v214, v1, s[2:3]
	v_lshlrev_b32_e32 v92, 2, v1
	v_xor_b32_e32 v1, 32, v214
	v_cmp_lt_i32_e64 s[2:3], v1, v0
	v_cmp_gt_u32_e32 vcc, 32, v10
	v_cmp_eq_u32_e64 s[4:5], 0, v10
	v_cndmask_b32_e64 v0, v214, v1, s[2:3]
	v_lshlrev_b32_e32 v93, 2, v0
	v_lshl_add_u64 v[0:1], v[2:3], 0, s[0:1]
	s_mov_b64 s[0:1], 0x3f6d0000
	v_lshl_add_u64 v[2:3], v[2:3], 0, s[0:1]
	s_lshl_b64 s[0:1], s[42:43], 12
	s_add_u32 s0, s44, s0
	s_addc_u32 s1, s45, s1
	v_lshl_add_u64 v[8:9], s[0:1], 0, v[128:129]
	s_mov_b64 s[0:1], 0x1fa0b000
	s_ashr_i32 s41, s40, 31
	v_lshlrev_b32_e32 v128, 4, v10
	v_cmp_gt_u32_e64 s[2:3], 16, v10
	v_cmp_eq_u32_e64 s[6:7], 1, v10
	v_cmp_eq_u32_e64 s[8:9], 2, v10
	v_cmp_eq_u32_e64 s[10:11], 3, v10
	v_cmp_eq_u32_e64 s[12:13], 4, v10
	v_cmp_eq_u32_e64 s[14:15], 5, v10
	v_cmp_eq_u32_e64 s[16:17], 6, v10
	v_cmp_eq_u32_e64 s[18:19], 7, v10
	v_cmp_eq_u32_e64 s[20:21], 8, v10
	v_cmp_eq_u32_e64 s[22:23], 9, v10
	v_cmp_eq_u32_e64 s[24:25], 10, v10
	v_cmp_eq_u32_e64 s[26:27], 11, v10
	v_cmp_eq_u32_e64 s[28:29], 12, v10
	v_cmp_eq_u32_e64 s[30:31], 13, v10
	v_cmp_eq_u32_e64 s[34:35], 14, v10
	v_cmp_eq_u32_e64 s[36:37], 15, v10
	v_lshl_add_u64 v[8:9], v[8:9], 0, s[0:1]
	s_lshl_b64 s[44:45], s[40:41], 12
	v_lshl_add_u64 v[10:11], s[38:39], 0, v[128:129]
	s_branch .LBB0_204

.LBB0_205:
	s_movk_i32 s0, 0xd000
	v_add_co_u32_e64 v80, s[38:39], s0, v76
	s_movk_i32 s0, 0xe000
	s_nop 0
	v_addc_co_u32_e64 v81, s[38:39], -1, v77, s[38:39]
	v_add_co_u32_e64 v84, s[38:39], s0, v76
	s_movk_i32 s0, 0xf000
	s_nop 0
	v_addc_co_u32_e64 v85, s[38:39], -1, v77, s[38:39]
	v_add_co_u32_e64 v98, s[38:39], s0, v76
	global_load_dwordx2 v[80:81], v[80:81], off
	s_nop 0
	v_addc_co_u32_e64 v99, s[38:39], -1, v77, s[38:39]
	global_load_dwordx2 v[84:85], v[84:85], off
	v_lshl_add_u64 v[156:157], v[6:7], 0, s[46:47]
	global_load_dwordx2 v[98:99], v[98:99], off
	s_add_u32 s46, s46, 0x4000
	global_load_dwordx4 v[160:163], v[74:75], off
	s_mov_b64 s[0:1], 0x200
	s_addc_u32 s47, s47, 0
	s_cmp_eq_u32 s46, 0x20000
	global_load_dwordx2 v[164:165], v[76:77], off
	v_add_u32_e32 v218, s46, v196
	ds_read_b128 v[166:169], v218
	v_add_u32_e32 v218, s46, v197
	ds_read_b128 v[170:173], v218
	v_add_u32_e32 v218, s46, v198
	ds_read_b128 v[102:105], v218
	v_add_u32_e32 v218, s46, v199
	ds_read_b128 v[106:109], v218
	v_add_u32_e32 v218, s46, v200
	ds_read_b128 v[110:113], v218
	v_add_u32_e32 v218, s46, v201
	ds_read_b128 v[114:117], v218
	v_add_u32_e32 v218, s46, v202
	ds_read_b128 v[118:121], v218
	v_add_u32_e32 v218, s46, v203
	ds_read_b128 v[122:125], v218
	v_add_u32_e32 v218, s46, v204
	ds_read_b128 v[130:133], v218
	v_add_u32_e32 v218, s46, v205
	ds_read_b128 v[134:137], v218
	v_add_u32_e32 v218, s46, v206
	ds_read_b128 v[138:141], v218
	v_add_u32_e32 v218, s46, v207
	ds_read_b128 v[142:145], v218
	v_add_u32_e32 v218, s46, v208
	ds_read_b128 v[146:149], v218
	v_add_u32_e32 v218, s46, v209
	ds_read_b128 v[174:177], v218
	v_add_u32_e32 v218, s46, v232
	ds_read_b128 v[178:181], v218
	v_add_u32_e32 v218, s46, v233
	ds_read_b128 v[182:185], v218
	s_waitcnt vmcnt(0) lgkmcnt(0)
	v_lshlrev_b32_e32 v86, 16, v84
	v_and_b32_e32 v87, 0xffff0000, v84
	v_lshlrev_b32_e32 v100, 16, v98
	v_and_b32_e32 v101, 0xffff0000, v98
	v_lshlrev_b32_e32 v98, 16, v99
	v_and_b32_e32 v99, 0xffff0000, v99
	v_pk_mul_f32 v[126:127], v[162:163], v[98:99]
	v_lshlrev_b32_e32 v82, 16, v80
	v_and_b32_e32 v83, 0xffff0000, v80
	v_lshlrev_b32_e32 v80, 16, v81
	v_and_b32_e32 v81, 0xffff0000, v81
	v_lshlrev_b32_e32 v84, 16, v85
	v_and_b32_e32 v85, 0xffff0000, v85
	v_pk_mul_f32 v[150:151], v[160:161], v[100:101]
	v_pk_mul_f32 v[80:81], v[162:163], v[80:81]
	v_pk_mul_f32 v[82:83], v[160:161], v[82:83]
	v_pk_mul_f32 v[84:85], v[162:163], v[84:85]
	v_pk_mul_f32 v[86:87], v[160:161], v[86:87]
	v_lshl_add_u64 v[76:77], v[76:77], 0, s[0:1]
	s_mov_b64 s[0:1], 0x400
	v_lshl_add_u64 v[74:75], v[74:75], 0, s[0:1]
	s_waitcnt vmcnt(0) lgkmcnt(0)
	v_lshlrev_b32_e32 v100, 16, v164
	v_and_b32_e32 v101, 0xffff0000, v164
	v_lshlrev_b32_e32 v98, 16, v165
	v_and_b32_e32 v99, 0xffff0000, v165
	v_pk_mul_f32 v[152:153], v[162:163], v[98:99]
	v_pk_mul_f32 v[154:155], v[160:161], v[100:101]
	s_waitcnt vmcnt(0) lgkmcnt(0)
	v_pk_fma_f32 v[78:79], v[166:167], v[82:83], v[78:79] op_sel_hi:[1,0,1]
	v_pk_fma_f32 v[72:73], v[168:169], v[82:83], v[72:73] op_sel_hi:[1,0,1]
	v_pk_fma_f32 v[58:59], v[166:167], v[86:87], v[58:59] op_sel_hi:[1,0,1]
	v_pk_fma_f32 v[56:57], v[168:169], v[86:87], v[56:57] op_sel_hi:[1,0,1]
	v_pk_fma_f32 v[42:43], v[166:167], v[150:151], v[42:43] op_sel_hi:[1,0,1]
	v_pk_fma_f32 v[40:41], v[168:169], v[150:151], v[40:41] op_sel_hi:[1,0,1]
	v_pk_fma_f32 v[26:27], v[166:167], v[154:155], v[26:27] op_sel_hi:[1,0,1]
	v_pk_fma_f32 v[24:25], v[168:169], v[154:155], v[24:25] op_sel_hi:[1,0,1]
	v_pk_fma_f32 v[70:71], v[170:171], v[82:83], v[70:71] op_sel_hi:[1,0,1]
	v_pk_fma_f32 v[68:69], v[172:173], v[82:83], v[68:69] op_sel_hi:[1,0,1]
	v_pk_fma_f32 v[54:55], v[170:171], v[86:87], v[54:55] op_sel_hi:[1,0,1]
	v_pk_fma_f32 v[52:53], v[172:173], v[86:87], v[52:53] op_sel_hi:[1,0,1]
	v_pk_fma_f32 v[38:39], v[170:171], v[150:151], v[38:39] op_sel_hi:[1,0,1]
	v_pk_fma_f32 v[36:37], v[172:173], v[150:151], v[36:37] op_sel_hi:[1,0,1]
	v_pk_fma_f32 v[22:23], v[170:171], v[154:155], v[22:23] op_sel_hi:[1,0,1]
	v_pk_fma_f32 v[20:21], v[172:173], v[154:155], v[20:21] op_sel_hi:[1,0,1]
	v_pk_fma_f32 v[70:71], v[82:83], v[114:115], v[70:71] op_sel:[1,0,0]
	v_pk_fma_f32 v[68:69], v[82:83], v[116:117], v[68:69] op_sel:[1,0,0]
	v_pk_fma_f32 v[54:55], v[114:115], v[86:87], v[54:55] op_sel:[0,1,0]
	v_pk_fma_f32 v[52:53], v[116:117], v[86:87], v[52:53] op_sel:[0,1,0]
	v_pk_fma_f32 v[38:39], v[114:115], v[150:151], v[38:39] op_sel:[0,1,0]
	v_pk_fma_f32 v[36:37], v[116:117], v[150:151], v[36:37] op_sel:[0,1,0]
	v_pk_fma_f32 v[22:23], v[114:115], v[154:155], v[22:23] op_sel:[0,1,0]
	v_pk_fma_f32 v[20:21], v[116:117], v[154:155], v[20:21] op_sel:[0,1,0]
	v_pk_fma_f32 v[70:71], v[80:81], v[134:135], v[70:71] op_sel_hi:[0,1,1]
	v_pk_fma_f32 v[68:69], v[80:81], v[136:137], v[68:69] op_sel_hi:[0,1,1]
	v_pk_fma_f32 v[54:55], v[84:85], v[134:135], v[54:55] op_sel_hi:[0,1,1]
	v_pk_fma_f32 v[52:53], v[84:85], v[136:137], v[52:53] op_sel_hi:[0,1,1]
	v_pk_fma_f32 v[38:39], v[126:127], v[134:135], v[38:39] op_sel_hi:[0,1,1]
	v_pk_fma_f32 v[36:37], v[126:127], v[136:137], v[36:37] op_sel_hi:[0,1,1]
	v_pk_fma_f32 v[22:23], v[152:153], v[134:135], v[22:23] op_sel_hi:[0,1,1]
	v_pk_fma_f32 v[20:21], v[152:153], v[136:137], v[20:21] op_sel_hi:[0,1,1]
	v_pk_fma_f32 v[66:67], v[102:103], v[82:83], v[66:67] op_sel_hi:[1,0,1]
	v_pk_fma_f32 v[64:65], v[104:105], v[82:83], v[64:65] op_sel_hi:[1,0,1]
	v_pk_fma_f32 v[50:51], v[102:103], v[86:87], v[50:51] op_sel_hi:[1,0,1]
	v_pk_fma_f32 v[48:49], v[104:105], v[86:87], v[48:49] op_sel_hi:[1,0,1]
	v_pk_fma_f32 v[34:35], v[102:103], v[150:151], v[34:35] op_sel_hi:[1,0,1]
	v_pk_fma_f32 v[32:33], v[104:105], v[150:151], v[32:33] op_sel_hi:[1,0,1]
	v_pk_fma_f32 v[18:19], v[102:103], v[154:155], v[18:19] op_sel_hi:[1,0,1]
	v_pk_fma_f32 v[12:13], v[104:105], v[154:155], v[12:13] op_sel_hi:[1,0,1]
	v_pk_fma_f32 v[66:67], v[82:83], v[118:119], v[66:67] op_sel:[1,0,0]
	v_pk_fma_f32 v[64:65], v[82:83], v[120:121], v[64:65] op_sel:[1,0,0]
	v_pk_fma_f32 v[50:51], v[86:87], v[118:119], v[50:51] op_sel:[1,0,0]
	v_pk_fma_f32 v[48:49], v[86:87], v[120:121], v[48:49] op_sel:[1,0,0]
	v_pk_fma_f32 v[34:35], v[118:119], v[150:151], v[34:35] op_sel:[0,1,0]
	v_pk_fma_f32 v[32:33], v[120:121], v[150:151], v[32:33] op_sel:[0,1,0]
	v_pk_fma_f32 v[18:19], v[118:119], v[154:155], v[18:19] op_sel:[0,1,0]
	v_pk_fma_f32 v[12:13], v[120:121], v[154:155], v[12:13] op_sel:[0,1,0]
	v_pk_fma_f32 v[66:67], v[80:81], v[138:139], v[66:67] op_sel_hi:[0,1,1]
	v_pk_fma_f32 v[64:65], v[80:81], v[140:141], v[64:65] op_sel_hi:[0,1,1]
	v_pk_fma_f32 v[50:51], v[84:85], v[138:139], v[50:51] op_sel_hi:[0,1,1]
	v_pk_fma_f32 v[48:49], v[84:85], v[140:141], v[48:49] op_sel_hi:[0,1,1]
	v_pk_fma_f32 v[34:35], v[126:127], v[138:139], v[34:35] op_sel_hi:[0,1,1]
	v_pk_fma_f32 v[32:33], v[126:127], v[140:141], v[32:33] op_sel_hi:[0,1,1]
	v_pk_fma_f32 v[18:19], v[152:153], v[138:139], v[18:19] op_sel_hi:[0,1,1]
	v_pk_fma_f32 v[12:13], v[152:153], v[140:141], v[12:13] op_sel_hi:[0,1,1]
	v_pk_fma_f32 v[62:63], v[106:107], v[82:83], v[62:63] op_sel_hi:[1,0,1]
	v_pk_fma_f32 v[60:61], v[108:109], v[82:83], v[60:61] op_sel_hi:[1,0,1]
	v_pk_fma_f32 v[46:47], v[106:107], v[86:87], v[46:47] op_sel_hi:[1,0,1]
	v_pk_fma_f32 v[44:45], v[108:109], v[86:87], v[44:45] op_sel_hi:[1,0,1]
	v_pk_fma_f32 v[30:31], v[106:107], v[150:151], v[30:31] op_sel_hi:[1,0,1]
	v_pk_fma_f32 v[28:29], v[108:109], v[150:151], v[28:29] op_sel_hi:[1,0,1]
	v_pk_fma_f32 v[16:17], v[106:107], v[154:155], v[16:17] op_sel_hi:[1,0,1]
	v_pk_fma_f32 v[14:15], v[108:109], v[154:155], v[14:15] op_sel_hi:[1,0,1]
	v_pk_fma_f32 v[78:79], v[110:111], v[82:83], v[78:79] op_sel:[0,1,0]
	v_pk_fma_f32 v[72:73], v[112:113], v[82:83], v[72:73] op_sel:[0,1,0]
	v_pk_fma_f32 v[58:59], v[110:111], v[86:87], v[58:59] op_sel:[0,1,0]
	v_pk_fma_f32 v[56:57], v[112:113], v[86:87], v[56:57] op_sel:[0,1,0]
	v_pk_fma_f32 v[42:43], v[110:111], v[150:151], v[42:43] op_sel:[0,1,0]
	v_pk_fma_f32 v[40:41], v[112:113], v[150:151], v[40:41] op_sel:[0,1,0]
	v_pk_fma_f32 v[26:27], v[110:111], v[154:155], v[26:27] op_sel:[0,1,0]
	v_pk_fma_f32 v[24:25], v[112:113], v[154:155], v[24:25] op_sel:[0,1,0]
	v_pk_fma_f32 v[62:63], v[82:83], v[122:123], v[62:63] op_sel:[1,0,0]
	v_pk_fma_f32 v[60:61], v[82:83], v[124:125], v[60:61] op_sel:[1,0,0]
	v_pk_fma_f32 v[46:47], v[86:87], v[122:123], v[46:47] op_sel:[1,0,0]
	v_pk_fma_f32 v[44:45], v[86:87], v[124:125], v[44:45] op_sel:[1,0,0]
	v_pk_fma_f32 v[30:31], v[150:151], v[122:123], v[30:31] op_sel:[1,0,0]
	v_pk_fma_f32 v[28:29], v[150:151], v[124:125], v[28:29] op_sel:[1,0,0]
	v_pk_fma_f32 v[16:17], v[122:123], v[154:155], v[16:17] op_sel:[0,1,0]
	v_pk_fma_f32 v[14:15], v[124:125], v[154:155], v[14:15] op_sel:[0,1,0]
	v_pk_fma_f32 v[78:79], v[80:81], v[130:131], v[78:79] op_sel_hi:[0,1,1]
	v_pk_fma_f32 v[72:73], v[80:81], v[132:133], v[72:73] op_sel_hi:[0,1,1]
	v_pk_fma_f32 v[58:59], v[84:85], v[130:131], v[58:59] op_sel_hi:[0,1,1]
	v_pk_fma_f32 v[56:57], v[84:85], v[132:133], v[56:57] op_sel_hi:[0,1,1]
	v_pk_fma_f32 v[42:43], v[126:127], v[130:131], v[42:43] op_sel_hi:[0,1,1]
	v_pk_fma_f32 v[40:41], v[126:127], v[132:133], v[40:41] op_sel_hi:[0,1,1]
	v_pk_fma_f32 v[26:27], v[152:153], v[130:131], v[26:27] op_sel_hi:[0,1,1]
	s_waitcnt vmcnt(0) lgkmcnt(0)
	v_pk_fma_f32 v[70:71], v[80:81], v[174:175], v[70:71] op_sel:[1,0,0]
	v_pk_fma_f32 v[68:69], v[80:81], v[176:177], v[68:69] op_sel:[1,0,0]
	v_pk_fma_f32 v[54:55], v[84:85], v[174:175], v[54:55] op_sel:[1,0,0]
	v_pk_fma_f32 v[52:53], v[84:85], v[176:177], v[52:53] op_sel:[1,0,0]
	v_pk_fma_f32 v[38:39], v[126:127], v[174:175], v[38:39] op_sel:[1,0,0]
	v_pk_fma_f32 v[36:37], v[126:127], v[176:177], v[36:37] op_sel:[1,0,0]
	v_pk_fma_f32 v[22:23], v[152:153], v[174:175], v[22:23] op_sel:[1,0,0]
	v_pk_fma_f32 v[20:21], v[152:153], v[176:177], v[20:21] op_sel:[1,0,0]
	v_pk_fma_f32 v[24:25], v[152:153], v[132:133], v[24:25] op_sel_hi:[0,1,1]
	v_pk_fma_f32 v[62:63], v[80:81], v[142:143], v[62:63] op_sel_hi:[0,1,1]
	v_pk_fma_f32 v[60:61], v[80:81], v[144:145], v[60:61] op_sel_hi:[0,1,1]
	v_pk_fma_f32 v[46:47], v[84:85], v[142:143], v[46:47] op_sel_hi:[0,1,1]
	v_pk_fma_f32 v[44:45], v[84:85], v[144:145], v[44:45] op_sel_hi:[0,1,1]
	v_pk_fma_f32 v[30:31], v[126:127], v[142:143], v[30:31] op_sel_hi:[0,1,1]
	v_pk_fma_f32 v[28:29], v[126:127], v[144:145], v[28:29] op_sel_hi:[0,1,1]
	v_pk_fma_f32 v[16:17], v[152:153], v[142:143], v[16:17] op_sel_hi:[0,1,1]
	v_pk_fma_f32 v[14:15], v[152:153], v[144:145], v[14:15] op_sel_hi:[0,1,1]
	v_pk_fma_f32 v[78:79], v[80:81], v[146:147], v[78:79] op_sel:[1,0,0]
	v_pk_fma_f32 v[72:73], v[80:81], v[148:149], v[72:73] op_sel:[1,0,0]
	v_pk_fma_f32 v[58:59], v[84:85], v[146:147], v[58:59] op_sel:[1,0,0]
	v_pk_fma_f32 v[56:57], v[84:85], v[148:149], v[56:57] op_sel:[1,0,0]
	v_pk_fma_f32 v[42:43], v[126:127], v[146:147], v[42:43] op_sel:[1,0,0]
	v_pk_fma_f32 v[40:41], v[126:127], v[148:149], v[40:41] op_sel:[1,0,0]
	v_pk_fma_f32 v[26:27], v[152:153], v[146:147], v[26:27] op_sel:[1,0,0]
	v_pk_fma_f32 v[24:25], v[152:153], v[148:149], v[24:25] op_sel:[1,0,0]
	s_waitcnt vmcnt(0) lgkmcnt(0)
	v_pk_fma_f32 v[66:67], v[80:81], v[178:179], v[66:67] op_sel:[1,0,0]
	v_pk_fma_f32 v[64:65], v[80:81], v[180:181], v[64:65] op_sel:[1,0,0]
	v_pk_fma_f32 v[50:51], v[84:85], v[178:179], v[50:51] op_sel:[1,0,0]
	v_pk_fma_f32 v[48:49], v[84:85], v[180:181], v[48:49] op_sel:[1,0,0]
	v_pk_fma_f32 v[34:35], v[126:127], v[178:179], v[34:35] op_sel:[1,0,0]
	v_pk_fma_f32 v[32:33], v[126:127], v[180:181], v[32:33] op_sel:[1,0,0]
	v_pk_fma_f32 v[18:19], v[152:153], v[178:179], v[18:19] op_sel:[1,0,0]
	v_pk_fma_f32 v[12:13], v[152:153], v[180:181], v[12:13] op_sel:[1,0,0]
	s_waitcnt vmcnt(0) lgkmcnt(0)
	v_pk_fma_f32 v[62:63], v[80:81], v[182:183], v[62:63] op_sel:[1,0,0]
	v_pk_fma_f32 v[60:61], v[80:81], v[184:185], v[60:61] op_sel:[1,0,0]
	v_pk_fma_f32 v[46:47], v[84:85], v[182:183], v[46:47] op_sel:[1,0,0]
	v_pk_fma_f32 v[44:45], v[84:85], v[184:185], v[44:45] op_sel:[1,0,0]
	v_pk_fma_f32 v[30:31], v[126:127], v[182:183], v[30:31] op_sel:[1,0,0]
	v_pk_fma_f32 v[28:29], v[126:127], v[184:185], v[28:29] op_sel:[1,0,0]
	v_pk_fma_f32 v[16:17], v[152:153], v[182:183], v[16:17] op_sel:[1,0,0]
	v_pk_fma_f32 v[14:15], v[152:153], v[184:185], v[14:15] op_sel:[1,0,0]
	s_cbranch_scc0 .LBB0_205
	s_ashr_i32 s43, s42, 31
	v_mov_b32_e32 v74, 0
	s_and_saveexec_b64 s[38:39], vcc
	s_cbranch_execz .LBB0_208
	s_lshl_b64 s[0:1], s[42:43], 7
	v_lshl_add_u64 v[74:75], v[0:1], 0, s[0:1]
	global_load_dword v74, v[74:75], off
